# E12 + softmax row sums via 16x16x32 MFMA with a selector B operand (half the matrix-pipe time of the 32x32x16 P*ones MFMA); O-layout sums rebuilt through per-wave LDS scratch before the epilogue
# speedup vs baseline: 1.0162x; 1.0141x over previous
; #define LAS __attribute__((address_space(3)))
;     __device__ __forceinline__ unsigned char* ws() const { return (unsigned char*)raw(25); }
; template <int TYPE> __device__ __forceinline__ void attn_unit(LAS unsigned char* lds, const AttnUnit& U) {
;     ...
;     f32x16 o0 = {}, o1 = {}, o2 = {}, negm = {}, p0 = {}, p1 = {};
;     u32x4 pw[4] = {};
;     const bf16x8 ones = {0x3F80, 0x3F80, 0x3F80, 0x3F80, 0x3F80, 0x3F80, 0x3F80, 0x3F80};
; __device__ __forceinline__ void attn_phase(const Ctx& a, LAS unsigned char* lds) {
;     unsigned char* ws = a.ws();
;     const bf16* PROJ = (const bf16*)(ws + WS_PROJ); const bf16* QM = (const bf16*)(ws + WS_QM); const bf16* KV = (const bf16*)(ws + WS_KV); const bf16* KROPE = (const bf16*)(ws + WS_KROPE);
;     const bf16* FKS = (const bf16*)(ws + WS_FKS); const bf16* FVS = (const bf16*)(ws + WS_FVS); const float* LKB = (const float*)(ws + WS_LK); bf16* OB = (bf16*)(ws + WS_XN);
;     unsigned* qctr = (unsigned*)(ws + WS_QCTR);
;     const int myx = (int)(__builtin_amdgcn_s_getreg((3 << 11) | 20) & 7u);
.LBB0_635:
	v_writelane_b32 v227, s92, 7
	s_nop 1
	v_writelane_b32 v227, s93, 8
	v_writelane_b32 v227, s91, 9
	v_writelane_b32 v227, s90, 10
	v_writelane_b32 v227, s89, 11
	v_writelane_b32 v227, s88, 12
	v_writelane_b32 v227, s87, 13
	v_writelane_b32 v227, s83, 14
	v_writelane_b32 v227, s86, 15
	s_nop 1
	v_writelane_b32 v227, s87, 16
	v_writelane_b32 v227, s84, 17
	s_nop 1
	v_writelane_b32 v227, s85, 18
	v_writelane_b32 v227, s82, 19
	v_writelane_b32 v227, s81, 20
	s_or_b64 exec, exec, s[0:1]
	s_add_i32 s0, 0, 0x200c8
	v_mov_b32_e32 v0, s0
	s_waitcnt lgkmcnt(0)
	s_barrier
	ds_read_b64 v[0:1], v0
	s_mov_b32 s97, 0
	s_getreg_b32 s16, hwreg(HW_REG_XCC_ID, 0, 4)
	v_mov_b32_e32 v185, 1
	v_and_b32_e32 v254, 63, v184
	v_bfe_u32 v252, v254, 4, 1
	v_and_b32_e32 v253, 15, v254
	v_mov_b32_e32 v248, 0x3f803f80
	v_cmp_eq_u32_e32 vcc, v253, v252
	s_nop 1
	v_cndmask_b32_e32 v248, 0, v248, vcc
	v_and_b32_e32 v252, 1, v254
	v_lshlrev_b32_e32 v252, 6, v252
	v_and_b32_e32 v255, 48, v254
	v_add_u32_e32 v252, v252, v255
	v_lshrrev_b32_e32 v255, 5, v254
	v_lshlrev_b32_e32 v255, 4, v255
	v_sub_u32_e32 v252, v252, v255
	v_and_b32_e32 v254, 0x1c0, v184
	v_lshlrev_b32_e32 v254, 2, v254
	v_add_u32_e32 v254, v254, v255
	v_add_u32_e32 v254, 0x14400, v254
	v_mov_b32_e32 v249, v248
	v_mov_b32_e32 v250, v248
	v_mov_b32_e32 v251, v248
	s_mov_b32 s90, 0x42200000
	s_waitcnt lgkmcnt(0)
	v_readfirstlane_b32 s1, v0
	v_readfirstlane_b32 s0, v1
	s_add_u32 s2, s1, 0x13497000
	v_writelane_b32 v227, s2, 21
	s_addc_u32 s2, s0, 0
	v_writelane_b32 v227, s2, 22
	s_add_u32 s2, s1, 0x295f7000
	v_writelane_b32 v227, s2, 23
	s_addc_u32 s2, s0, 0
	v_writelane_b32 v227, s2, 24
	s_add_u32 s2, s1, 0x2f657000
	v_writelane_b32 v227, s2, 25
	s_addc_u32 s2, s0, 0
	v_writelane_b32 v227, s2, 26
	s_add_u32 s2, s1, 0x2d93000
	v_writelane_b32 v227, s2, 27
	s_addc_u32 s2, s0, 0
	v_writelane_b32 v227, s2, 28
	s_add_u32 s2, s1, 0xe437000
	v_writelane_b32 v227, s2, 29
	s_addc_u32 s2, s0, 0
	v_writelane_b32 v227, s2, 30
	s_add_u32 s2, s1, 0x10467000
	v_writelane_b32 v227, s2, 31
	s_addc_u32 s2, s0, 0
	v_writelane_b32 v227, s2, 32
	s_add_u32 s2, s1, 0x2990000
	v_writelane_b32 v227, s2, 33
	s_addc_u32 s2, s0, 0
	v_writelane_b32 v227, s2, 34
	s_add_u32 s2, s1, 0x3397000
	v_writelane_b32 v227, s2, 35
	s_addc_u32 s2, s0, 0
	v_writelane_b32 v227, s2, 36
	s_add_u32 s2, s1, 0x3b6d7000
	s_addc_u32 s3, s0, 0
	v_writelane_b32 v227, s2, 37
	v_mov_b32_e32 v1, 0
	s_mov_b32 s76, 0x3f803f80
	v_writelane_b32 v227, s3, 38
	s_add_u32 s2, s1, 0x2890000
	s_addc_u32 s3, s0, 0
	v_writelane_b32 v227, s2, 39
	s_add_i32 s0, 0, 0x20100
	v_mov_b32_e32 v186, s0
	v_writelane_b32 v227, s3, 40
	v_writelane_b32 v227, s0, 41
	s_add_i32 s0, 0, 0x14100
	v_writelane_b32 v227, s0, 42
	s_add_i32 s0, 0, 0x14200
	v_writelane_b32 v227, s0, 43
	s_add_i32 s0, 0, 0x14300
	v_writelane_b32 v227, s0, 44
	s_add_i32 s0, 0, 0x1000
	v_writelane_b32 v227, s0, 45
	s_add_i32 s0, 0, 0x800
	s_add_i32 s93, 0, 0x14000
	v_writelane_b32 v227, s0, 46
	s_movk_i32 s37, 0x7fff
	v_mov_b32_e32 v187, 0x100
	v_mov_b32_e32 v188, 0xff800000
	v_mov_b32_e32 v189, 0x2000
	v_mov_b32_e32 v190, 0
	v_writelane_b32 v227, s93, 47
	v_writelane_b32 v227, s16, 48
	s_branch .LBB0_637

; #define LAS __attribute__((address_space(3)))
; template <int TYPE> __device__ __forceinline__ void attn_unit(LAS unsigned char* lds, const AttnUnit& U) {
;     ...
;         float mt; A_ROWMAX(s0, s1, mt);
;         bool resc = false;
;         if (__any(mt > THR)) {
;             const float dl = fmaxf(mt, 0.f); mref += dl;
; #pragma unroll
;             for (int r = 0; r < 16; ++r) { s0[r] -= dl; s1[r] -= dl; if (TYPE == 0) negm[r] = -mref; }
;             if (hi == 0) wsf[r32] = __builtin_amdgcn_exp2f(-dl);
;             resc = true;
;         }
;         A_PV(sk2, true, s0, s1);
;         if (resc) {
;             asm volatile("s_waitcnt lgkmcnt(0)" ::: "memory");
; #pragma unroll
;             for (int g = 0; g < 4; ++g) { const f32x4 al = *(const LAS f32x4*)(wsf + 8 * g + 4 * hi);
; #pragma unroll
;                 for (int i = 0; i < 4; ++i) { o0[4 * g + i] *= al[i]; o1[4 * g + i] *= al[i]; o2[4 * g + i] *= al[i]; } }
.LBB0_678:
	s_lshl_b32 s6, s77, 13
	s_add_i32 s6, s6, 0xc000
	v_add_u32_e32 v0, s6, v174
	v_add_u32_e32 v14, s6, v173
	ds_read_b64_tr_b16 v[2:3], v0
	ds_read_b64_tr_b16 v[4:5], v0 offset:1024
	ds_read_b64_tr_b16 v[6:7], v14
	ds_read_b64_tr_b16 v[8:9], v14 offset:1024
	ds_read_b64_tr_b16 v[178:179], v0 offset:2048
	ds_read_b64_tr_b16 v[180:181], v0 offset:3072
	ds_read_b64_tr_b16 v[192:193], v14 offset:2048
	ds_read_b64_tr_b16 v[194:195], v14 offset:3072
	v_mfma_f32_16x16x32_bf16 v[48:51], v[148:151], v[248:251], v[48:51]
	v_max_f32_e32 v236, v96, v97
	v_max3_f32 v237, v98, v99, v113
	v_max3_f32 v236, v236, v112, v114
	v_max3_f32 v236, v236, v115, v100
	v_max3_f32 v237, v237, v102, v103
	s_waitcnt lgkmcnt(6)
	v_mfma_f32_32x32x16_bf16 v[32:47], v[148:151], v[2:5], v[32:47]
	v_max3_f32 v236, v236, v101, v116
	v_max3_f32 v237, v237, v118, v119
	v_max3_f32 v236, v236, v117, v104
	v_max3_f32 v237, v237, v106, v107
	v_max3_f32 v236, v236, v105, v120
	v_max3_f32 v237, v237, v122, v123
	s_waitcnt lgkmcnt(4)
	v_mfma_f32_32x32x16_bf16 v[16:31], v[148:151], v[6:9], v[16:31]
	v_max3_f32 v236, v236, v121, v108
	v_max3_f32 v237, v237, v110, v111
	v_max3_f32 v236, v236, v109, v124
	v_max3_f32 v237, v237, v126, v127
	v_max3_f32 v236, v236, v125, v237
	v_cmp_lt_f32_e32 vcc, s90, v236
	s_cmp_lg_u64 vcc, 0
	s_cselect_b64 s[72:73], -1, 0
	s_cbranch_vccz .LBB0_682
	v_mov_b32_e32 v237, v236
	s_nop 1
	v_permlane32_swap_b32_e32 v236, v237
	v_max_f32_e32 v237, v237, v237
	v_max_f32_e32 v236, v236, v236
	v_max_f32_e32 v236, v236, v237
	v_max_f32_e32 v236, v236, v236
	v_max_f32_e32 v236, 0, v236
	s_and_saveexec_b64 s[78:79], s[4:5]
	v_exp_f32_e64 v237, -v236
	ds_write_b32 v176, v237
	s_or_b64 exec, exec, s[78:79]
	v_sub_f32_e32 v111, v111, v236
	v_sub_f32_e32 v110, v110, v236
	v_sub_f32_e32 v109, v109, v236
	v_sub_f32_e32 v108, v108, v236
	v_sub_f32_e32 v107, v107, v236
	v_sub_f32_e32 v106, v106, v236
	v_sub_f32_e32 v105, v105, v236
	v_sub_f32_e32 v104, v104, v236
	v_sub_f32_e32 v103, v103, v236
	v_sub_f32_e32 v102, v102, v236
	v_sub_f32_e32 v101, v101, v236
	v_sub_f32_e32 v100, v100, v236
	v_sub_f32_e32 v99, v99, v236
	v_sub_f32_e32 v98, v98, v236
	v_sub_f32_e32 v97, v97, v236
	v_sub_f32_e32 v96, v96, v236
	v_sub_f32_e32 v127, v127, v236
	v_sub_f32_e32 v126, v126, v236
	v_sub_f32_e32 v125, v125, v236
	v_sub_f32_e32 v124, v124, v236
	v_sub_f32_e32 v123, v123, v236
	v_sub_f32_e32 v122, v122, v236
	v_sub_f32_e32 v121, v121, v236
	v_sub_f32_e32 v120, v120, v236
	v_sub_f32_e32 v119, v119, v236
	v_sub_f32_e32 v118, v118, v236
	v_sub_f32_e32 v117, v117, v236
	v_sub_f32_e32 v116, v116, v236
	v_sub_f32_e32 v115, v115, v236
	v_sub_f32_e32 v114, v114, v236
	v_sub_f32_e32 v113, v113, v236
	v_sub_f32_e32 v112, v112, v236
	v_add_f32_e32 v160, v160, v236
.LBB0_682:
	v_exp_f32_e32 v64, v96
	v_exp_f32_e32 v65, v97
	v_exp_f32_e32 v80, v112
	v_mfma_f32_16x16x32_bf16 v[48:51], v[152:155], v[248:251], v[48:51]
	ds_read_b64_tr_b16 v[2:3], v0 offset:4096
	ds_read_b64_tr_b16 v[4:5], v0 offset:5120
	ds_read_b64_tr_b16 v[6:7], v14 offset:4096
	ds_read_b64_tr_b16 v[8:9], v14 offset:5120
	v_exp_f32_e32 v66, v98
	v_exp_f32_e32 v81, v113
	v_exp_f32_e32 v82, v114
	v_exp_f32_e32 v67, v99
	s_waitcnt lgkmcnt(6)
	v_mfma_f32_32x32x16_bf16 v[32:47], v[152:155], v[178:181], v[32:47]
	v_exp_f32_e32 v83, v115
	v_exp_f32_e32 v68, v100
	v_exp_f32_e32 v69, v101
	v_exp_f32_e32 v84, v116
	s_waitcnt lgkmcnt(4)
	v_mfma_f32_32x32x16_bf16 v[16:31], v[152:155], v[192:195], v[16:31]
	v_exp_f32_e32 v70, v102
	v_exp_f32_e32 v85, v117
	v_exp_f32_e32 v86, v118
	v_exp_f32_e32 v71, v103
	v_mfma_f32_16x16x32_bf16 v[48:51], v[156:159], v[248:251], v[48:51]
	ds_read_b64_tr_b16 v[228:229], v0 offset:6144
	ds_read_b64_tr_b16 v[230:231], v0 offset:7168
	ds_read_b64_tr_b16 v[232:233], v14 offset:6144
	ds_read_b64_tr_b16 v[234:235], v14 offset:7168
	v_exp_f32_e32 v87, v119
	v_exp_f32_e32 v72, v104
	v_exp_f32_e32 v73, v105
	s_waitcnt lgkmcnt(6)
	v_mfma_f32_32x32x16_bf16 v[32:47], v[156:159], v[2:5], v[32:47]
	v_exp_f32_e32 v88, v120
	v_exp_f32_e32 v74, v106
	v_exp_f32_e32 v89, v121
	s_waitcnt lgkmcnt(4)
	v_mfma_f32_32x32x16_bf16 v[16:31], v[156:159], v[6:9], v[16:31]
	v_exp_f32_e32 v90, v122
	v_exp_f32_e32 v75, v107
	v_exp_f32_e32 v91, v123
	v_mfma_f32_16x16x32_bf16 v[48:51], v[144:147], v[248:251], v[48:51]
	v_exp_f32_e32 v76, v108
	v_exp_f32_e32 v77, v109
	v_exp_f32_e32 v92, v124
	s_waitcnt lgkmcnt(2)
	v_mfma_f32_32x32x16_bf16 v[32:47], v[144:147], v[228:231], v[32:47]
	v_exp_f32_e32 v78, v110
	v_exp_f32_e32 v93, v125
	v_exp_f32_e32 v94, v126
	s_waitcnt lgkmcnt(0)
	v_mfma_f32_32x32x16_bf16 v[16:31], v[144:147], v[232:235], v[16:31]
	v_exp_f32_e32 v79, v111
	v_exp_f32_e32 v95, v127
	s_andn2_b64 vcc, exec, s[72:73]
	s_cbranch_vccnz .LBB0_684
	s_waitcnt lgkmcnt(0)
	ds_read_b128 v[2:5], v177 offset:96
	ds_read_b128 v[6:9], v177 offset:64
	ds_read_b128 v[10:13], v177 offset:32
	ds_read_b128 v[96:99], v177
	s_waitcnt lgkmcnt(0)
	s_waitcnt lgkmcnt(3)
	v_pk_mul_f32 v[46:47], v[46:47], v[4:5]
	s_waitcnt lgkmcnt(2)
	v_pk_mul_f32 v[42:43], v[42:43], v[8:9]
	s_waitcnt lgkmcnt(1)
	v_pk_mul_f32 v[38:39], v[38:39], v[12:13]
	s_waitcnt lgkmcnt(0)
	v_pk_mul_f32 v[34:35], v[34:35], v[98:99]
	v_pk_mul_f32 v[44:45], v[44:45], v[2:3]
	v_pk_mul_f32 v[40:41], v[40:41], v[6:7]
	v_pk_mul_f32 v[36:37], v[36:37], v[10:11]
	v_pk_mul_f32 v[32:33], v[32:33], v[96:97]
	v_pk_mul_f32 v[30:31], v[30:31], v[4:5]
	v_pk_mul_f32 v[26:27], v[26:27], v[8:9]
	v_pk_mul_f32 v[22:23], v[22:23], v[12:13]
	v_pk_mul_f32 v[18:19], v[18:19], v[98:99]
	v_pk_mul_f32 v[28:29], v[28:29], v[2:3]
	v_pk_mul_f32 v[24:25], v[24:25], v[6:7]
	v_pk_mul_f32 v[20:21], v[20:21], v[10:11]
	v_pk_mul_f32 v[16:17], v[16:17], v[96:97]
	v_add_u32_e32 v14, v254, v252
	ds_read_b128 v[100:103], v14
	s_waitcnt lgkmcnt(0)
	v_pk_mul_f32 v[48:49], v[48:49], v[100:101]
	v_pk_mul_f32 v[50:51], v[50:51], v[102:103]

; #define A_PACK() do { _Pragma("unroll") for (int c = 0; c < 16; ++c) A_PK1(c); } while (0)
; #define A_TOP(t, d1_, d2_) do { if ((((t)) & 1) == 0) { A_DMAK((t) + 2, ((t) + 2) & 3); A_DMAK((t) + 3, ((t) + 3) & 3); A_DMAV((t) + 1, ((t) + 1) & 3); A_DMAV((t) + 2, ((t) + 2) & 3); } } while (0)
; #define A_BOT() do { if (t & 1) { A_WAITBAR(0); } } while (0)
; #define A_ROT() do { sk = (t + 1) & 3; sk2 = t & 3; } while (0)
; template <int TYPE> __device__ __forceinline__ void attn_unit(LAS unsigned char* lds, const AttnUnit& U) {
;     ...
;     if (NTw > 0) {
;         A_TOP(t, sk2, sk1);
;         A_PACK();
;         A_PV(sk2, false, p0, p1);
;         A_BOT(); A_ROT();
.LBB0_691:
	v_add_u32_e32 v0, s8, v174
	v_cvt_pk_bf16_f32 v2, v64, v65
	v_cvt_pk_bf16_f32 v3, v66, v67
	v_cvt_pk_bf16_f32 v4, v68, v69
	v_cvt_pk_bf16_f32 v5, v70, v71
	v_add_u32_e32 v14, s8, v173
	ds_read_b64_tr_b16 v[64:65], v0
	ds_read_b64_tr_b16 v[66:67], v0 offset:1024
	ds_read_b64_tr_b16 v[68:69], v14
	ds_read_b64_tr_b16 v[70:71], v14 offset:1024
	v_cvt_pk_bf16_f32 v6, v72, v73
	v_cvt_pk_bf16_f32 v7, v74, v75
	v_cvt_pk_bf16_f32 v8, v76, v77
	v_cvt_pk_bf16_f32 v9, v78, v79
	v_cvt_pk_bf16_f32 v10, v80, v81
	v_cvt_pk_bf16_f32 v11, v82, v83
	v_cvt_pk_bf16_f32 v12, v84, v85
	v_cvt_pk_bf16_f32 v13, v86, v87
	v_cvt_pk_bf16_f32 v72, v88, v89
	v_cvt_pk_bf16_f32 v73, v90, v91
	v_cvt_pk_bf16_f32 v74, v92, v93
	v_cvt_pk_bf16_f32 v75, v94, v95
	s_mov_b32 s77, s76
	s_mov_b32 s78, s76
	s_mov_b32 s79, s76
	v_mov_b64_e32 v[76:77], s[76:77]
	v_mov_b64_e32 v[78:79], s[78:79]
	ds_read_b64_tr_b16 v[80:81], v0 offset:2048
	ds_read_b64_tr_b16 v[82:83], v0 offset:3072
	ds_read_b64_tr_b16 v[84:85], v14 offset:2048
	ds_read_b64_tr_b16 v[86:87], v14 offset:3072
	v_mfma_f32_16x16x32_bf16 v[48:51], v[2:5], v[248:251], v[48:51]
	s_waitcnt lgkmcnt(6)
	v_mfma_f32_32x32x16_bf16 v[32:47], v[2:5], v[64:67], v[32:47]
	s_waitcnt lgkmcnt(4)
	v_mfma_f32_32x32x16_bf16 v[16:31], v[2:5], v[68:71], v[16:31]
	v_mfma_f32_16x16x32_bf16 v[48:51], v[6:9], v[248:251], v[48:51]
	ds_read_b64_tr_b16 v[2:3], v0 offset:4096
	ds_read_b64_tr_b16 v[4:5], v0 offset:5120
	ds_read_b64_tr_b16 v[64:65], v14 offset:4096
	ds_read_b64_tr_b16 v[66:67], v14 offset:5120
	s_waitcnt lgkmcnt(6)
	v_mfma_f32_32x32x16_bf16 v[32:47], v[6:9], v[80:83], v[32:47]
	s_waitcnt lgkmcnt(4)
	v_mfma_f32_32x32x16_bf16 v[16:31], v[6:9], v[84:87], v[16:31]
	v_mfma_f32_16x16x32_bf16 v[48:51], v[10:13], v[248:251], v[48:51]
	ds_read_b64_tr_b16 v[6:7], v0 offset:6144
	ds_read_b64_tr_b16 v[8:9], v0 offset:7168
	ds_read_b64_tr_b16 v[68:69], v14 offset:6144
	ds_read_b64_tr_b16 v[70:71], v14 offset:7168
	s_waitcnt lgkmcnt(6)
	v_mfma_f32_32x32x16_bf16 v[32:47], v[10:13], v[2:5], v[32:47]
	s_waitcnt lgkmcnt(4)
	v_mfma_f32_32x32x16_bf16 v[16:31], v[10:13], v[64:67], v[16:31]
	v_mfma_f32_16x16x32_bf16 v[48:51], v[72:75], v[248:251], v[48:51]
	s_waitcnt lgkmcnt(2)
	v_mfma_f32_32x32x16_bf16 v[32:47], v[72:75], v[6:9], v[32:47]
	s_waitcnt lgkmcnt(0)
	v_mfma_f32_32x32x16_bf16 v[16:31], v[72:75], v[68:71], v[16:31]
	s_andn2_b64 vcc, exec, s[6:7]
	s_cbranch_vccnz .LBB0_693
	s_waitcnt vmcnt(0) lgkmcnt(0)
	s_barrier

; #define GAS __attribute__((address_space(1)))
; __device__ __forceinline__ unsigned f2bf(float f) { unsigned u = __builtin_bit_cast(unsigned, f); return (u + 0x7fffu + ((u >> 16) & 1u)) >> 16; }
; __device__ __forceinline__ int crow(int r, int hi) { return (r & 3) + 8 * (r >> 2) + 4 * hi; }
; template <int TYPE> __device__ __forceinline__ void attn_unit(LAS unsigned char* lds, const AttnUnit& U) {
;     ...
;     asm volatile("s_waitcnt vmcnt(0)" ::: "memory");
;     if (active) {
; #pragma unroll
;         for (int r = 0; r < 16; ++r) { const int q = wid * 32 + crow(r, hi);
;             if (q < U.nq) { const float il = __builtin_amdgcn_rcpf(o2[r]); GAS bf16* op = (GAS bf16*)(U.O + (size_t)q * DM + r32); op[0] = (bf16)f2bf(o0[r] * il); op[32] = (bf16)f2bf(o1[r] * il); } }
.LBB0_701:
	v_readlane_b32 s2, v226, 31
	s_waitcnt vmcnt(0)
	v_readlane_b32 s3, v226, 32
	s_andn2_b64 vcc, exec, s[2:3]
	s_cbranch_vccnz .LBB0_735
	v_cmp_gt_u32_e32 vcc, 2, v253
	v_add_u32_e32 v0, v254, v252
	s_and_saveexec_b64 s[2:3], vcc
	ds_write_b128 v0, v[48:51]
	s_or_b64 exec, exec, s[2:3]
	s_waitcnt lgkmcnt(0)
	ds_read_b128 v[48:51], v254
	ds_read_b128 v[52:55], v254 offset:32
	ds_read_b128 v[56:59], v254 offset:64
	ds_read_b128 v[60:63], v254 offset:96
	s_waitcnt lgkmcnt(0)
	v_readlane_b32 s2, v226, 26
	v_lshlrev_b32_e32 v0, 1, v161
	v_readlane_b32 s3, v226, 27
	v_or_b32_e32 v4, s25, v168
	v_cmp_gt_i32_e32 vcc, s20, v4
	v_lshl_add_u64 v[2:3], s[2:3], 0, v[0:1]
	s_and_saveexec_b64 s[2:3], vcc
	s_cbranch_execz .LBB0_704
	v_rcp_f32_e32 v0, v48
	v_ashrrev_i32_e32 v5, 31, v4
	v_lshlrev_b64 v[6:7], 11, v[4:5]
	v_lshl_add_u64 v[6:7], v[2:3], 0, v[6:7]
	v_mul_f32_e32 v5, v0, v32
	v_bfe_u32 v8, v5, 16, 1
	v_add3_u32 v5, v5, v8, s37
	v_mul_f32_e32 v0, v16, v0
	global_store_short_d16_hi v[6:7], v5, off
	v_bfe_u32 v5, v0, 16, 1
	v_add3_u32 v0, v0, v5, s37
	global_store_short_d16_hi v[6:7], v0, off offset:64

; #define LAS __attribute__((address_space(3)))
; template <int TYPE> __device__ __forceinline__ void attn_unit(LAS unsigned char* lds, const AttnUnit& U) {
;     ...
;         float mt; A_ROWMAX(s0, s1, mt);
;         bool resc = false;
;         if (__any(mt > THR)) {
;             const float dl = fmaxf(mt, 0.f); mref += dl;
; #pragma unroll
;             for (int r = 0; r < 16; ++r) { s0[r] -= dl; s1[r] -= dl; if (TYPE == 0) negm[r] = -mref; }
;             if (hi == 0) wsf[r32] = __builtin_amdgcn_exp2f(-dl);
;             resc = true;
;         }
;         A_PV(sk2, true, s0, s1);
;         if (resc) {
;             asm volatile("s_waitcnt lgkmcnt(0)" ::: "memory");
; #pragma unroll
;             for (int g = 0; g < 4; ++g) { const f32x4 al = *(const LAS f32x4*)(wsf + 8 * g + 4 * hi);
; #pragma unroll
;                 for (int i = 0; i < 4; ++i) { o0[4 * g + i] *= al[i]; o1[4 * g + i] *= al[i]; o2[4 * g + i] *= al[i]; } }
.LBB0_750:
	s_lshl_b32 s77, s77, 13
	s_add_i32 s77, s77, 0xc000
	v_add_u32_e32 v0, s77, v200
	v_add_u32_e32 v14, s77, v201
	ds_read_b64_tr_b16 v[2:3], v0
	ds_read_b64_tr_b16 v[4:5], v0 offset:1024
	ds_read_b64_tr_b16 v[6:7], v14
	ds_read_b64_tr_b16 v[8:9], v14 offset:1024
	ds_read_b64_tr_b16 v[212:213], v0 offset:2048
	ds_read_b64_tr_b16 v[214:215], v0 offset:3072
	ds_read_b64_tr_b16 v[216:217], v14 offset:2048
	ds_read_b64_tr_b16 v[218:219], v14 offset:3072
	v_mfma_f32_16x16x32_bf16 v[48:51], v[172:175], v[248:251], v[48:51]
	v_max_f32_e32 v236, v128, v129
	v_max3_f32 v237, v130, v131, v113
	v_max3_f32 v236, v236, v112, v114
	v_max3_f32 v236, v236, v115, v132
	v_max3_f32 v237, v237, v134, v135
	s_waitcnt lgkmcnt(6)
	v_mfma_f32_32x32x16_bf16 v[32:47], v[172:175], v[2:5], v[32:47]
	v_max3_f32 v236, v236, v133, v116
	v_max3_f32 v237, v237, v118, v119
	v_max3_f32 v236, v236, v117, v136
	v_max3_f32 v237, v237, v138, v139
	v_max3_f32 v236, v236, v137, v120
	v_max3_f32 v237, v237, v122, v123
	s_waitcnt lgkmcnt(4)
	v_mfma_f32_32x32x16_bf16 v[16:31], v[172:175], v[6:9], v[16:31]
	v_max3_f32 v236, v236, v121, v140
	v_max3_f32 v237, v237, v142, v143
	v_max3_f32 v236, v236, v141, v124
	v_max3_f32 v237, v237, v126, v127
	v_max3_f32 v236, v236, v125, v237
	v_cmp_lt_f32_e32 vcc, s90, v236
	s_cmp_lg_u64 vcc, 0
	s_cselect_b64 s[72:73], -1, 0
	s_cbranch_vccz .LBB0_754
	v_mov_b32_e32 v237, v236
	s_nop 1
	v_permlane32_swap_b32_e32 v236, v237
	v_max_f32_e32 v237, v237, v237
	v_max_f32_e32 v236, v236, v236
	v_max_f32_e32 v236, v236, v237
	v_max_f32_e32 v236, v236, v236
	v_max_f32_e32 v236, 0, v236
	s_and_saveexec_b64 s[78:79], s[4:5]
	v_exp_f32_e64 v237, -v236
	ds_write_b32 v209, v237
	s_or_b64 exec, exec, s[78:79]
	v_add_f32_e32 v202, v202, v236
	v_xor_b32_e32 v96, 0x80000000, v202
	v_sub_f32_e32 v143, v143, v236
	v_sub_f32_e32 v142, v142, v236
	v_sub_f32_e32 v141, v141, v236
	v_sub_f32_e32 v140, v140, v236
	v_sub_f32_e32 v139, v139, v236
	v_sub_f32_e32 v138, v138, v236
	v_sub_f32_e32 v137, v137, v236
	v_sub_f32_e32 v136, v136, v236
	v_sub_f32_e32 v135, v135, v236
	v_sub_f32_e32 v134, v134, v236
	v_sub_f32_e32 v133, v133, v236
	v_sub_f32_e32 v132, v132, v236
	v_sub_f32_e32 v131, v131, v236
	v_sub_f32_e32 v130, v130, v236
	v_sub_f32_e32 v129, v129, v236
	v_sub_f32_e32 v128, v128, v236
	v_sub_f32_e32 v127, v127, v236
	v_sub_f32_e32 v126, v126, v236
	v_sub_f32_e32 v125, v125, v236
	v_sub_f32_e32 v124, v124, v236
	v_sub_f32_e32 v123, v123, v236
	v_sub_f32_e32 v122, v122, v236
	v_sub_f32_e32 v121, v121, v236
	v_sub_f32_e32 v120, v120, v236
	v_sub_f32_e32 v119, v119, v236
	v_sub_f32_e32 v118, v118, v236
	v_sub_f32_e32 v117, v117, v236
	v_sub_f32_e32 v116, v116, v236
	v_sub_f32_e32 v115, v115, v236
	v_sub_f32_e32 v114, v114, v236
	v_sub_f32_e32 v113, v113, v236
	v_sub_f32_e32 v112, v112, v236
	v_mov_b32_e32 v97, v96
	v_mov_b32_e32 v98, v96
	v_mov_b32_e32 v99, v96
	v_mov_b32_e32 v100, v96
	v_mov_b32_e32 v101, v96
	v_mov_b32_e32 v102, v96
	v_mov_b32_e32 v103, v96
	v_mov_b32_e32 v104, v96
	v_mov_b32_e32 v105, v96
	v_mov_b32_e32 v106, v96
	v_mov_b32_e32 v107, v96
	v_mov_b32_e32 v108, v96
	v_mov_b32_e32 v109, v96
	v_mov_b32_e32 v110, v96
	v_mov_b32_e32 v111, v96
.LBB0_754:
	v_exp_f32_e32 v80, v128
	v_exp_f32_e32 v81, v129
	v_exp_f32_e32 v64, v112
	v_mfma_f32_16x16x32_bf16 v[48:51], v[176:179], v[248:251], v[48:51]
	ds_read_b64_tr_b16 v[2:3], v0 offset:4096
	ds_read_b64_tr_b16 v[4:5], v0 offset:5120
	ds_read_b64_tr_b16 v[6:7], v14 offset:4096
	ds_read_b64_tr_b16 v[8:9], v14 offset:5120
	v_exp_f32_e32 v82, v130
	v_exp_f32_e32 v65, v113
	v_exp_f32_e32 v66, v114
	v_exp_f32_e32 v83, v131
	s_waitcnt lgkmcnt(6)
	v_mfma_f32_32x32x16_bf16 v[32:47], v[176:179], v[212:215], v[32:47]
	v_exp_f32_e32 v67, v115
	v_exp_f32_e32 v84, v132
	v_exp_f32_e32 v85, v133
	v_exp_f32_e32 v68, v116
	s_waitcnt lgkmcnt(4)
	v_mfma_f32_32x32x16_bf16 v[16:31], v[176:179], v[216:219], v[16:31]
	v_exp_f32_e32 v86, v134
	v_exp_f32_e32 v69, v117
	v_exp_f32_e32 v70, v118
	v_exp_f32_e32 v87, v135
	v_mfma_f32_16x16x32_bf16 v[48:51], v[180:183], v[248:251], v[48:51]
	ds_read_b64_tr_b16 v[228:229], v0 offset:6144
	ds_read_b64_tr_b16 v[230:231], v0 offset:7168
	ds_read_b64_tr_b16 v[232:233], v14 offset:6144
	ds_read_b64_tr_b16 v[234:235], v14 offset:7168
	v_exp_f32_e32 v71, v119
	v_exp_f32_e32 v88, v136
	v_exp_f32_e32 v89, v137
	s_waitcnt lgkmcnt(6)
	v_mfma_f32_32x32x16_bf16 v[32:47], v[180:183], v[2:5], v[32:47]
	v_exp_f32_e32 v72, v120
	v_exp_f32_e32 v90, v138
	v_exp_f32_e32 v73, v121
	s_waitcnt lgkmcnt(4)
	v_mfma_f32_32x32x16_bf16 v[16:31], v[180:183], v[6:9], v[16:31]
	v_exp_f32_e32 v74, v122
	v_exp_f32_e32 v91, v139
	v_exp_f32_e32 v75, v123
	v_mfma_f32_16x16x32_bf16 v[48:51], v[168:171], v[248:251], v[48:51]
	v_exp_f32_e32 v92, v140
	v_exp_f32_e32 v93, v141
	v_exp_f32_e32 v76, v124
	s_waitcnt lgkmcnt(2)
	v_mfma_f32_32x32x16_bf16 v[32:47], v[168:171], v[228:231], v[32:47]
	v_exp_f32_e32 v94, v142
	v_exp_f32_e32 v77, v125
	v_exp_f32_e32 v78, v126
	s_waitcnt lgkmcnt(0)
	v_mfma_f32_32x32x16_bf16 v[16:31], v[168:171], v[232:235], v[16:31]
	v_exp_f32_e32 v95, v143
	v_exp_f32_e32 v79, v127
	s_andn2_b64 vcc, exec, s[72:73]
	s_cbranch_vccnz .LBB0_756
	s_waitcnt lgkmcnt(0)
	ds_read_b128 v[2:5], v210 offset:96
	ds_read_b128 v[6:9], v210 offset:64
	ds_read_b128 v[10:13], v210 offset:32
	ds_read_b128 v[112:115], v210
	s_waitcnt lgkmcnt(0)
	s_waitcnt lgkmcnt(3)
	v_pk_mul_f32 v[46:47], v[46:47], v[4:5]
	s_waitcnt lgkmcnt(2)
	v_pk_mul_f32 v[42:43], v[42:43], v[8:9]
	s_waitcnt lgkmcnt(1)
	v_pk_mul_f32 v[38:39], v[38:39], v[12:13]
	s_waitcnt lgkmcnt(0)
	v_pk_mul_f32 v[34:35], v[34:35], v[114:115]
	v_pk_mul_f32 v[44:45], v[44:45], v[2:3]
	v_pk_mul_f32 v[40:41], v[40:41], v[6:7]
	v_pk_mul_f32 v[36:37], v[36:37], v[10:11]
	v_pk_mul_f32 v[32:33], v[32:33], v[112:113]
	v_pk_mul_f32 v[30:31], v[30:31], v[4:5]
	v_pk_mul_f32 v[26:27], v[26:27], v[8:9]
	v_pk_mul_f32 v[22:23], v[22:23], v[12:13]
	v_pk_mul_f32 v[18:19], v[18:19], v[114:115]
	v_pk_mul_f32 v[28:29], v[28:29], v[2:3]
	v_pk_mul_f32 v[24:25], v[24:25], v[6:7]
	v_pk_mul_f32 v[20:21], v[20:21], v[10:11]
	v_pk_mul_f32 v[16:17], v[16:17], v[112:113]
	v_add_u32_e32 v14, v254, v252
	ds_read_b128 v[116:119], v14
	s_waitcnt lgkmcnt(0)
	v_pk_mul_f32 v[48:49], v[48:49], v[116:117]
	v_pk_mul_f32 v[50:51], v[50:51], v[118:119]

; #define A_PACK() do { _Pragma("unroll") for (int c = 0; c < 16; ++c) A_PK1(c); } while (0)
; #define A_TOP(t, d1_, d2_) do { if ((((t)) & 1) == 0) { A_DMAK((t) + 2, ((t) + 2) & 3); A_DMAK((t) + 3, ((t) + 3) & 3); A_DMAV((t) + 1, ((t) + 1) & 3); A_DMAV((t) + 2, ((t) + 2) & 3); } } while (0)
; #define A_BOT() do { if (t & 1) { A_WAITBAR(0); } } while (0)
; #define A_ROT() do { sk = (t + 1) & 3; sk2 = t & 3; } while (0)
; template <int TYPE> __device__ __forceinline__ void attn_unit(LAS unsigned char* lds, const AttnUnit& U) {
;     ...
;     if (NTw > 0) {
;         A_TOP(t, sk2, sk1);
;         A_PACK();
;         A_PV(sk2, false, p0, p1);
;         A_BOT(); A_ROT();
.LBB0_763:
	v_add_u32_e32 v0, s8, v200
	v_cvt_pk_bf16_f32 v10, v64, v65
	v_cvt_pk_bf16_f32 v11, v66, v67
	v_cvt_pk_bf16_f32 v12, v68, v69
	v_cvt_pk_bf16_f32 v13, v70, v71
	v_add_u32_e32 v14, s8, v201
	ds_read_b64_tr_b16 v[64:65], v0
	ds_read_b64_tr_b16 v[66:67], v0 offset:1024
	ds_read_b64_tr_b16 v[68:69], v14
	ds_read_b64_tr_b16 v[70:71], v14 offset:1024
	v_cvt_pk_bf16_f32 v2, v80, v81
	v_cvt_pk_bf16_f32 v3, v82, v83
	v_cvt_pk_bf16_f32 v4, v84, v85
	v_cvt_pk_bf16_f32 v5, v86, v87
	v_cvt_pk_bf16_f32 v6, v88, v89
	v_cvt_pk_bf16_f32 v7, v90, v91
	v_cvt_pk_bf16_f32 v8, v92, v93
	v_cvt_pk_bf16_f32 v9, v94, v95
	v_cvt_pk_bf16_f32 v72, v72, v73
	v_cvt_pk_bf16_f32 v73, v74, v75
	v_cvt_pk_bf16_f32 v74, v76, v77
	v_cvt_pk_bf16_f32 v75, v78, v79
	s_mov_b32 s77, s76
	s_mov_b32 s78, s76
	s_mov_b32 s79, s76
	v_mov_b64_e32 v[76:77], s[76:77]
	v_mov_b64_e32 v[78:79], s[78:79]
	ds_read_b64_tr_b16 v[80:81], v0 offset:2048
	ds_read_b64_tr_b16 v[82:83], v0 offset:3072
	ds_read_b64_tr_b16 v[84:85], v14 offset:2048
	ds_read_b64_tr_b16 v[86:87], v14 offset:3072
	v_mfma_f32_16x16x32_bf16 v[48:51], v[2:5], v[248:251], v[48:51]
	s_waitcnt lgkmcnt(6)
	v_mfma_f32_32x32x16_bf16 v[32:47], v[2:5], v[64:67], v[32:47]
	s_waitcnt lgkmcnt(4)
	v_mfma_f32_32x32x16_bf16 v[16:31], v[2:5], v[68:71], v[16:31]
	v_mfma_f32_16x16x32_bf16 v[48:51], v[6:9], v[248:251], v[48:51]
	ds_read_b64_tr_b16 v[2:3], v0 offset:4096
	ds_read_b64_tr_b16 v[4:5], v0 offset:5120
	ds_read_b64_tr_b16 v[64:65], v14 offset:4096
	ds_read_b64_tr_b16 v[66:67], v14 offset:5120
	s_waitcnt lgkmcnt(6)
	v_mfma_f32_32x32x16_bf16 v[32:47], v[6:9], v[80:83], v[32:47]
	s_waitcnt lgkmcnt(4)
	v_mfma_f32_32x32x16_bf16 v[16:31], v[6:9], v[84:87], v[16:31]
	v_mfma_f32_16x16x32_bf16 v[48:51], v[10:13], v[248:251], v[48:51]
	ds_read_b64_tr_b16 v[6:7], v0 offset:6144
	ds_read_b64_tr_b16 v[8:9], v0 offset:7168
	ds_read_b64_tr_b16 v[68:69], v14 offset:6144
	ds_read_b64_tr_b16 v[70:71], v14 offset:7168
	s_waitcnt lgkmcnt(6)
	v_mfma_f32_32x32x16_bf16 v[32:47], v[10:13], v[2:5], v[32:47]
	s_waitcnt lgkmcnt(4)
	v_mfma_f32_32x32x16_bf16 v[16:31], v[10:13], v[64:67], v[16:31]
	v_mfma_f32_16x16x32_bf16 v[48:51], v[72:75], v[248:251], v[48:51]
	s_waitcnt lgkmcnt(2)
	v_mfma_f32_32x32x16_bf16 v[32:47], v[72:75], v[6:9], v[32:47]
	s_waitcnt lgkmcnt(0)
	v_mfma_f32_32x32x16_bf16 v[16:31], v[72:75], v[68:71], v[16:31]
	s_andn2_b64 vcc, exec, s[6:7]
	s_cbranch_vccnz .LBB0_765
	s_waitcnt vmcnt(0) lgkmcnt(0)
	s_barrier

; #define GAS __attribute__((address_space(1)))
; __device__ __forceinline__ unsigned f2bf(float f) { unsigned u = __builtin_bit_cast(unsigned, f); return (u + 0x7fffu + ((u >> 16) & 1u)) >> 16; }
; __device__ __forceinline__ int crow(int r, int hi) { return (r & 3) + 8 * (r >> 2) + 4 * hi; }
; template <int TYPE> __device__ __forceinline__ void attn_unit(LAS unsigned char* lds, const AttnUnit& U) {
;     ...
;     asm volatile("s_waitcnt vmcnt(0)" ::: "memory");
;     if (active) {
; #pragma unroll
;         for (int r = 0; r < 16; ++r) { const int q = wid * 32 + crow(r, hi);
;             if (q < U.nq) { const float il = __builtin_amdgcn_rcpf(o2[r]); GAS bf16* op = (GAS bf16*)(U.O + (size_t)q * DM + r32); op[0] = (bf16)f2bf(o0[r] * il); op[32] = (bf16)f2bf(o1[r] * il); } }
.LBB0_773:
	v_readlane_b32 s0, v226, 31
	s_waitcnt vmcnt(0)
	v_readlane_b32 s1, v226, 32
	s_andn2_b64 vcc, exec, s[0:1]
	s_cbranch_vccnz .LBB0_650
	v_cmp_gt_u32_e32 vcc, 2, v253
	v_add_u32_e32 v0, v254, v252
	s_and_saveexec_b64 s[0:1], vcc
	ds_write_b128 v0, v[48:51]
	s_or_b64 exec, exec, s[0:1]
	s_waitcnt lgkmcnt(0)
	ds_read_b128 v[48:51], v254
	ds_read_b128 v[52:55], v254 offset:32
	ds_read_b128 v[56:59], v254 offset:64
	ds_read_b128 v[60:63], v254 offset:96
	s_waitcnt lgkmcnt(0)
	v_readlane_b32 s0, v226, 26
	v_lshlrev_b32_e32 v0, 1, v192
	v_readlane_b32 s1, v226, 27
	v_or_b32_e32 v4, s25, v199
	v_cmp_gt_i32_e32 vcc, s20, v4
	v_lshl_add_u64 v[2:3], s[0:1], 0, v[0:1]
	s_and_saveexec_b64 s[0:1], vcc
	s_cbranch_execz .LBB0_776
	v_rcp_f32_e32 v0, v48
	v_ashrrev_i32_e32 v5, 31, v4
	v_lshlrev_b64 v[6:7], 11, v[4:5]
	v_lshl_add_u64 v[6:7], v[2:3], 0, v[6:7]
	v_mul_f32_e32 v5, v0, v32
	v_bfe_u32 v8, v5, 16, 1
	v_add3_u32 v5, v5, v8, s37
	v_mul_f32_e32 v0, v16, v0
	global_store_short_d16_hi v[6:7], v5, off
	v_bfe_u32 v5, v0, 16, 1
	v_add3_u32 v0, v0, v5, s37
	global_store_short_d16_hi v[6:7], v0, off offset:64

; __global__ void __launch_bounds__(512, 2) mega_fwd(Args a) {
	.amdhsa_kernel _Z8mega_fwd4Args
		.amdhsa_group_segment_fixed_size 0
		.amdhsa_private_segment_fixed_size 0
		.amdhsa_kernarg_size 464
		.amdhsa_user_sgpr_count 2
		.amdhsa_user_sgpr_dispatch_ptr 0
		.amdhsa_user_sgpr_queue_ptr 0
		.amdhsa_user_sgpr_kernarg_segment_ptr 1
		.amdhsa_user_sgpr_dispatch_id 0
		.amdhsa_user_sgpr_kernarg_preload_length 0
		.amdhsa_user_sgpr_kernarg_preload_offset 0
		.amdhsa_user_sgpr_private_segment_size 0
		.amdhsa_uses_dynamic_stack 0
		.amdhsa_enable_private_segment 0
		.amdhsa_system_sgpr_workgroup_id_x 1
		.amdhsa_system_sgpr_workgroup_id_y 0
		.amdhsa_system_sgpr_workgroup_id_z 0
		.amdhsa_system_sgpr_workgroup_info 0
		.amdhsa_system_vgpr_workitem_id 2
		.amdhsa_next_free_vgpr 256
		.amdhsa_next_free_sgpr 98
		.amdhsa_accum_offset 256
		.amdhsa_reserve_vcc 1
		.amdhsa_float_round_mode_32 0
		.amdhsa_float_round_mode_16_64 0
		.amdhsa_float_denorm_mode_32 3
		.amdhsa_float_denorm_mode_16_64 3
		.amdhsa_dx10_clamp 1
		.amdhsa_ieee_mode 1
		.amdhsa_fp16_overflow 0
		.amdhsa_tg_split 0
		.amdhsa_exception_fp_ieee_invalid_op 0
		.amdhsa_exception_fp_denorm_src 0
		.amdhsa_exception_fp_ieee_div_zero 0
		.amdhsa_exception_fp_ieee_overflow 0
		.amdhsa_exception_fp_ieee_underflow 0
		.amdhsa_exception_fp_ieee_inexact 0
		.amdhsa_exception_int_div_zero 0
	.end_amdhsa_kernel

; __global__ void __launch_bounds__(512, 2) mega_fwd(Args a) {
amdhsa.kernels:
  - .agpr_count:     0
    .args:
      - .offset:         0
        .size:           208
        .value_kind:     by_value
      - .offset:         208
        .size:           4
        .value_kind:     hidden_block_count_x
      - .offset:         212
        .size:           4
        .value_kind:     hidden_block_count_y
      - .offset:         216
        .size:           4
        .value_kind:     hidden_block_count_z
      - .offset:         220
        .size:           2
        .value_kind:     hidden_group_size_x
      - .offset:         222
        .size:           2
        .value_kind:     hidden_group_size_y
      - .offset:         224
        .size:           2
        .value_kind:     hidden_group_size_z
      - .offset:         226
        .size:           2
        .value_kind:     hidden_remainder_x
      - .offset:         228
        .size:           2
        .value_kind:     hidden_remainder_y
      - .offset:         230
        .size:           2
        .value_kind:     hidden_remainder_z
      - .offset:         248
        .size:           8
        .value_kind:     hidden_global_offset_x
      - .offset:         256
        .size:           8
        .value_kind:     hidden_global_offset_y
      - .offset:         264
        .size:           8
        .value_kind:     hidden_global_offset_z
      - .offset:         272
        .size:           2
        .value_kind:     hidden_grid_dims
      - .offset:         296
        .size:           8
        .value_kind:     hidden_multigrid_sync_arg
      - .offset:         328
        .size:           4
        .value_kind:     hidden_dynamic_lds_size
    .group_segment_fixed_size: 0
    .kernarg_segment_align: 8
    .kernarg_segment_size: 464
    .language:       OpenCL C
    .language_version:
      - 2
      - 0
    .max_flat_workgroup_size: 512
    .name:           _Z8mega_fwd4Args
    .private_segment_fixed_size: 0
    .sgpr_count:     104
    .sgpr_spill_count: 131
    .symbol:         _Z8mega_fwd4Args.kd
    .uniform_work_group_size: 1
    .uses_dynamic_stack: false
    .vgpr_count:     256
    .vgpr_spill_count: 0
    .wavefront_size: 64
